# hand-written dense64 and MLA dense96 tile-loop heads aligned to 64 bytes (.p2align 6); otherwise v23
# baseline (speedup 1.0000x reference)
.Lam96_sk2_c:
	v_add_u32_e32 v138, s3, v134
	v_mad_i64_i32 v[140:141], s[42:43], v138, s82, 0
	v_mov_b32_e32 v142, s90
	v_mov_b32_e32 v143, s91
	v_lshl_add_u64 v[140:141], v[140:141], 1, v[142:143]
	v_lshl_add_u64 v[140:141], v[140:141], 0, s[0:1]
	v_lshl_add_u64 v[244:245], v[140:141], 0, v[0:1]
	v_mov_b32_e32 v136, s11
	v_mov_b32_e32 v137, 0
	v_sub_f32_e32 v216, 0, v132
	v_sub_f32_e32 v217, 0, v132
	v_sub_f32_e32 v218, 0, v132
	v_sub_f32_e32 v219, 0, v132
	v_sub_f32_e32 v220, 0, v132
	v_sub_f32_e32 v221, 0, v132
	v_sub_f32_e32 v222, 0, v132
	v_sub_f32_e32 v223, 0, v132
	v_sub_f32_e32 v224, 0, v132
	v_sub_f32_e32 v225, 0, v132
	v_sub_f32_e32 v226, 0, v132
	v_sub_f32_e32 v227, 0, v132
	v_sub_f32_e32 v228, 0, v132
	v_sub_f32_e32 v229, 0, v132
	v_sub_f32_e32 v230, 0, v132
	v_sub_f32_e32 v231, 0, v132
	s_add_i32 s10, s25, -1
	s_bitcmp1_b32 s10, 0
	s_cselect_b32 s2, 0x5000, 0
	v_add_u32_e32 v138, s2, v125
	v_add_u32_e32 v139, s2, v126
	.p2align 6

.Lad64_noprio:
	v_add_u32_e32 v134, s3, v118
	v_mad_i64_i32 v[246:247], s[26:27], v134, s82, 0
	v_mov_b32_e32 v208, s86
	v_mov_b32_e32 v209, s87
	v_lshl_add_u64 v[208:209], v[246:247], 1, v[208:209]
	v_lshl_add_u64 v[208:209], v[208:209], 0, s[0:1]
	v_lshl_add_u64 v[240:241], v[92:93], 1, v[208:209]
	v_add_u32_e32 v134, s3, v117
	v_mad_i64_i32 v[246:247], s[26:27], v134, s82, 0
	v_mov_b32_e32 v208, s90
	v_mov_b32_e32 v209, s91
	v_lshl_add_u64 v[208:209], v[246:247], 1, v[208:209]
	v_lshl_add_u64 v[208:209], v[208:209], 0, s[0:1]
	v_lshl_add_u64 v[242:243], v[208:209], 0, v[0:1]
	s_lshl_b32 s26, s82, 7
	v_mov_b32_e32 v244, s26
	v_mov_b32_e32 v245, 0
	v_mov_b32_e32 v239, v118
	s_mov_b32 s2, 0x41000000
	v_sub_f32_e32 v118, 0, v112
	v_sub_f32_e32 v119, 0, v112
	v_sub_f32_e32 v120, 0, v112
	v_sub_f32_e32 v121, 0, v112
	v_sub_f32_e32 v122, 0, v112
	v_sub_f32_e32 v123, 0, v112
	v_sub_f32_e32 v124, 0, v112
	v_sub_f32_e32 v125, 0, v112
	v_sub_f32_e32 v126, 0, v112
	v_sub_f32_e32 v127, 0, v112
	v_sub_f32_e32 v128, 0, v112
	v_sub_f32_e32 v129, 0, v112
	v_sub_f32_e32 v130, 0, v112
	v_sub_f32_e32 v131, 0, v112
	v_sub_f32_e32 v132, 0, v112
	v_sub_f32_e32 v133, 0, v112
	s_add_i32 s25, s24, 0xffffc000
	s_and_b32 s25, s25, 0x4000
	v_add_u32_e32 v134, s25, v98
	v_add_u32_e32 v117, s25, v109
	v_add_u32_e32 v208, s25, v111
	v_add_u32_e32 v209, s25, v114
	.p2align 6
